# stack11: stack10 + attention QK^T: all 8 K-fragment LDS reads issued up front into dead registers, 16 MFMAs with counted lgkmcnt waits (no per-step LDS round trip)
# baseline (speedup 1.0000x reference)
.LBB0_709:
	s_bitcmp1_b32 s46, 0
	s_cselect_b32 s46, 0x9000, 0
	s_add_i32 s51, s46, 0
	v_add3_u32 v108, s51, v209, v211
	ds_read_b128 v[96:99], v108
	ds_read_b128 v[104:107], v108 offset:64
	ds_read_b128 v[112:115], v108 offset:2304
	ds_read_b128 v[116:119], v108 offset:2368
	ds_read_b128 v[120:123], v108 offset:4608
	ds_read_b128 v[140:143], v108 offset:4672
	ds_read_b128 v[144:147], v108 offset:6912
	ds_read_b128 v[148:151], v108 offset:6976
	s_mov_b64 s[46:47], -1
	s_and_b64 vcc, exec, s[42:43]
	s_waitcnt lgkmcnt(7)
	v_mfma_f32_16x16x32_bf16 v[160:163], v[96:99], v[32:35], 0
	v_mfma_f32_16x16x32_bf16 v[124:127], v[96:99], v[40:43], 0
	s_waitcnt lgkmcnt(6)
	v_mfma_f32_16x16x32_bf16 v[124:127], v[104:107], v[44:47], v[124:127]
	v_mfma_f32_16x16x32_bf16 v[160:163], v[104:107], v[36:39], v[160:163]
	s_waitcnt lgkmcnt(5)
	v_mfma_f32_16x16x32_bf16 v[164:167], v[112:115], v[32:35], 0
	v_mfma_f32_16x16x32_bf16 v[128:131], v[112:115], v[40:43], 0
	s_waitcnt lgkmcnt(4)
	v_mfma_f32_16x16x32_bf16 v[128:131], v[116:119], v[44:47], v[128:131]
	v_mfma_f32_16x16x32_bf16 v[164:167], v[116:119], v[36:39], v[164:167]
	s_waitcnt lgkmcnt(3)
	v_mfma_f32_16x16x32_bf16 v[168:171], v[120:123], v[32:35], 0
	v_mfma_f32_16x16x32_bf16 v[132:135], v[120:123], v[40:43], 0
	s_waitcnt lgkmcnt(2)
	v_mfma_f32_16x16x32_bf16 v[132:135], v[140:143], v[44:47], v[132:135]
	v_mfma_f32_16x16x32_bf16 v[168:171], v[140:143], v[36:39], v[168:171]
	s_waitcnt lgkmcnt(1)
	v_mfma_f32_16x16x32_bf16 v[136:139], v[144:147], v[40:43], 0
	v_mfma_f32_16x16x32_bf16 v[172:175], v[144:147], v[32:35], 0
	s_waitcnt lgkmcnt(0)
	v_mfma_f32_16x16x32_bf16 v[172:175], v[148:151], v[36:39], v[172:175]
	v_mfma_f32_16x16x32_bf16 v[136:139], v[148:151], v[44:47], v[136:139]
	s_cbranch_vccz .LBB0_711
	s_nop 3
	v_max_f32_e32 v96, v160, v160
	v_max_f32_e32 v97, v161, v161
	v_max_f32_e32 v96, v96, v97
	v_max3_f32 v96, v96, v162, v163
	v_max3_f32 v96, v96, v164, v165
	v_max3_f32 v96, v96, v166, v167
	v_and_b32_e32 v98, 64, v229
	v_max3_f32 v96, v96, v168, v169
	v_xor_b32_e32 v97, 16, v229
	v_add_u32_e32 v98, 64, v98
	v_max3_f32 v96, v96, v170, v171
	v_cmp_lt_i32_e32 vcc, v97, v98
	v_max3_f32 v96, v96, v172, v173
	v_max3_f32 v96, v96, v174, v175
	v_cndmask_b32_e32 v97, v229, v97, vcc
	v_lshlrev_b32_e32 v97, 2, v97
	ds_bpermute_b32 v97, v97, v96
	s_waitcnt lgkmcnt(0)
	v_max_f32_e32 v97, v97, v97
	v_max_f32_e32 v96, v96, v97
	v_xor_b32_e32 v97, 32, v229
	v_cmp_lt_i32_e32 vcc, v97, v98
	s_nop 1
	v_cndmask_b32_e32 v97, v229, v97, vcc
	v_lshlrev_b32_e32 v97, 2, v97
	ds_bpermute_b32 v97, v97, v96
	s_waitcnt lgkmcnt(0)
	v_max3_f32 v214, v217, v96, v97
	v_sub_f32_e32 v96, v160, v214
	v_exp_f32_e32 v140, v96
	v_sub_f32_e32 v98, v161, v214
	v_exp_f32_e32 v141, v98
	v_sub_f32_e32 v98, v162, v214
	v_exp_f32_e32 v142, v98
	v_sub_f32_e32 v98, v163, v214
	v_exp_f32_e32 v143, v98
	v_sub_f32_e32 v98, v164, v214
	v_add_f32_e32 v97, 0, v140
	v_exp_f32_e32 v144, v98
	v_sub_f32_e32 v98, v165, v214
	v_add_f32_e32 v97, v141, v97
	v_exp_f32_e32 v145, v98
	v_sub_f32_e32 v98, v166, v214
	v_add_f32_e32 v97, v142, v97
	v_exp_f32_e32 v146, v98
	v_sub_f32_e32 v98, v167, v214
	v_add_f32_e32 v97, v143, v97
	v_exp_f32_e32 v147, v98
	v_sub_f32_e32 v98, v168, v214
	v_add_f32_e32 v97, v144, v97
	v_exp_f32_e32 v152, v98
	v_sub_f32_e32 v98, v169, v214
	v_add_f32_e32 v97, v145, v97
	v_exp_f32_e32 v153, v98
	v_sub_f32_e32 v98, v170, v214
	v_add_f32_e32 v97, v146, v97
	v_exp_f32_e32 v154, v98
	v_sub_f32_e32 v98, v171, v214
	v_add_f32_e32 v97, v147, v97
	v_exp_f32_e32 v155, v98
	v_sub_f32_e32 v98, v172, v214
	v_add_f32_e32 v97, v152, v97
	v_exp_f32_e32 v156, v98
	v_sub_f32_e32 v98, v173, v214
	v_add_f32_e32 v97, v153, v97
	v_exp_f32_e32 v157, v98
	v_sub_f32_e32 v98, v174, v214
	v_add_f32_e32 v97, v154, v97
	v_exp_f32_e32 v158, v98
	v_sub_f32_e32 v98, v175, v214
	v_sub_f32_e32 v96, v217, v214
	v_add_f32_e32 v97, v155, v97
	v_exp_f32_e32 v159, v98
	v_add_f32_e32 v97, v156, v97
	v_exp_f32_e32 v96, v96
	v_add_f32_e32 v97, v157, v97
	v_add_f32_e32 v97, v158, v97
	v_add_f32_e32 v215, v159, v97
	v_fmac_f32_e32 v215, v216, v96
	v_pk_mul_f32 v[150:151], v[94:95], v[96:97] op_sel_hi:[1,0]
	v_pk_mul_f32 v[148:149], v[92:93], v[96:97] op_sel_hi:[1,0]
	v_pk_mul_f32 v[122:123], v[90:91], v[96:97] op_sel_hi:[1,0]
	v_pk_mul_f32 v[120:121], v[88:89], v[96:97] op_sel_hi:[1,0]
	v_pk_mul_f32 v[118:119], v[82:83], v[96:97] op_sel_hi:[1,0]
	v_pk_mul_f32 v[116:117], v[80:81], v[96:97] op_sel_hi:[1,0]
	v_pk_mul_f32 v[114:115], v[70:71], v[96:97] op_sel_hi:[1,0]
	v_pk_mul_f32 v[112:113], v[68:69], v[96:97] op_sel_hi:[1,0]
	v_pk_mul_f32 v[110:111], v[66:67], v[96:97] op_sel_hi:[1,0]
	v_pk_mul_f32 v[108:109], v[64:65], v[96:97] op_sel_hi:[1,0]
	v_pk_mul_f32 v[106:107], v[74:75], v[96:97] op_sel_hi:[1,0]
	v_pk_mul_f32 v[104:105], v[72:73], v[96:97] op_sel_hi:[1,0]
	v_pk_mul_f32 v[102:103], v[78:79], v[96:97] op_sel_hi:[1,0]
	v_pk_mul_f32 v[100:101], v[76:77], v[96:97] op_sel_hi:[1,0]
	v_pk_mul_f32 v[98:99], v[86:87], v[96:97] op_sel_hi:[1,0]
	v_pk_mul_f32 v[96:97], v[84:85], v[96:97] op_sel_hi:[1,0]
	s_cbranch_execnz .LBB0_713
	s_branch .LBB0_712
